# G1/G6 tiles: k-tile 1 DMA issued together with k-tile 0 (first-tile preamble and previous tile's epilogue) so the pipeline fill overlaps the epilogue
# baseline (speedup 1.0000x reference)
.LBB0_119:
	s_lshl_b32 s46, s20, 7
	s_ashr_i32 s47, s46, 31
	s_andn2_b64 vcc, exec, s[50:51]
	s_lshl_b64 s[50:51], s[46:47], 11
	s_cbranch_vccnz .LBB0_121
	v_mov_b32_e32 v1, v168
	v_readlane_b32 s2, v252, 32
	v_readlane_b32 s3, v252, 33
	v_ashrrev_i32_e32 v4, 3, v1
	s_add_u32 s2, s2, s50
	v_xor_b32_e32 v3, v4, v1
	v_ashrrev_i32_e32 v5, 31, v4
	s_addc_u32 s3, s3, s51
	v_lshlrev_b64 v[4:5], 11, v[4:5]
	v_lshlrev_b32_e32 v3, 4, v3
	v_lshlrev_b32_e32 v1, 4, v1
	s_ashr_i32 s43, s42, 31
	s_waitcnt lgkmcnt(0)
	v_lshl_add_u64 v[6:7], s[2:3], 0, v[4:5]
	v_and_b32_e32 v8, 0x70, v3
	v_mov_b32_e32 v9, v2
	v_readfirstlane_b32 s2, v1
	v_add_u32_e32 v3, 0x1000, v1
	s_lshl_b64 s[52:53], s[42:43], 11
	v_readlane_b32 s1, v252, 34
	v_lshl_add_u64 v[6:7], v[6:7], 0, v[8:9]
	s_mov_b32 m0, s2
	v_readfirstlane_b32 s2, v3
	v_add_u32_e32 v3, 0x2000, v1
	s_add_u32 s20, s1, s52
	v_readlane_b32 s1, v252, 35
	global_load_lds_dwordx4 v[6:7], off
	v_lshl_add_u64 v[10:11], v[6:7], 0, s[24:25]
	s_mov_b32 m0, s2
	v_readfirstlane_b32 s2, v3
	v_add_u32_e32 v3, 0x3000, v1
	s_addc_u32 s21, s1, s53
	global_load_lds_dwordx4 v[10:11], off
	v_lshl_add_u64 v[10:11], v[6:7], 0, s[26:27]
	s_mov_b32 m0, s2
	v_readfirstlane_b32 s2, v3
	v_add_u32_e32 v3, 0x4000, v1
	v_lshl_add_u64 v[4:5], s[20:21], 0, v[4:5]
	global_load_lds_dwordx4 v[10:11], off
	v_lshl_add_u64 v[6:7], v[6:7], 0, s[28:29]
	s_mov_b32 m0, s2
	v_readfirstlane_b32 s2, v3
	v_add_u32_e32 v3, 0x5000, v1
	global_load_lds_dwordx4 v[6:7], off
	v_lshl_add_u64 v[4:5], v[4:5], 0, v[8:9]
	s_mov_b32 m0, s2
	v_readfirstlane_b32 s2, v3
	v_add_u32_e32 v3, 0x6000, v1
	global_load_lds_dwordx4 v[4:5], off
	v_lshl_add_u64 v[6:7], v[4:5], 0, s[24:25]
	s_mov_b32 m0, s2
	v_readfirstlane_b32 s2, v3
	v_add_u32_e32 v1, 0x7000, v1
	global_load_lds_dwordx4 v[6:7], off
	v_lshl_add_u64 v[6:7], v[4:5], 0, s[26:27]
	s_mov_b32 m0, s2
	v_readfirstlane_b32 s2, v1
	global_load_lds_dwordx4 v[6:7], off
	v_lshl_add_u64 v[4:5], v[4:5], 0, s[28:29]
	s_mov_b32 m0, s2
	s_nop 0
	global_load_lds_dwordx4 v[4:5], off
	v_mov_b32_e32 v1, v168
	v_readlane_b32 s2, v252, 32
	v_readlane_b32 s3, v252, 33
	v_ashrrev_i32_e32 v4, 3, v1
	s_add_u32 s2, s2, s50
	v_xor_b32_e32 v3, v4, v1
	v_ashrrev_i32_e32 v5, 31, v4
	s_addc_u32 s3, s3, s51
	s_add_u32 s2, s2, 0x80
	s_addc_u32 s3, s3, 0
	v_lshlrev_b64 v[4:5], 11, v[4:5]
	v_lshlrev_b32_e32 v3, 4, v3
	v_lshlrev_b32_e32 v1, 4, v1
	s_ashr_i32 s43, s42, 31
	s_waitcnt lgkmcnt(0)
	v_lshl_add_u64 v[6:7], s[2:3], 0, v[4:5]
	v_and_b32_e32 v8, 0x70, v3
	v_mov_b32_e32 v9, v2
	v_readfirstlane_b32 s2, v1
	v_add_u32_e32 v3, 0x1000, v1
	s_lshl_b64 s[52:53], s[42:43], 11
	v_readlane_b32 s1, v252, 34
	v_lshl_add_u64 v[6:7], v[6:7], 0, v[8:9]
	s_mov_b32 m0, s2
	s_bitset1_b32 m0, 15
	v_readfirstlane_b32 s2, v3
	v_add_u32_e32 v3, 0x2000, v1
	s_add_u32 s20, s1, s52
	v_readlane_b32 s1, v252, 35
	global_load_lds_dwordx4 v[6:7], off
	v_lshl_add_u64 v[10:11], v[6:7], 0, s[24:25]
	s_mov_b32 m0, s2
	s_bitset1_b32 m0, 15
	v_readfirstlane_b32 s2, v3
	v_add_u32_e32 v3, 0x3000, v1
	s_addc_u32 s21, s1, s53
	s_add_u32 s20, s20, 0x80
	s_addc_u32 s21, s21, 0
	global_load_lds_dwordx4 v[10:11], off
	v_lshl_add_u64 v[10:11], v[6:7], 0, s[26:27]
	s_mov_b32 m0, s2
	s_bitset1_b32 m0, 15
	v_readfirstlane_b32 s2, v3
	v_add_u32_e32 v3, 0x4000, v1
	v_lshl_add_u64 v[4:5], s[20:21], 0, v[4:5]
	global_load_lds_dwordx4 v[10:11], off
	v_lshl_add_u64 v[6:7], v[6:7], 0, s[28:29]
	s_mov_b32 m0, s2
	s_bitset1_b32 m0, 15
	v_readfirstlane_b32 s2, v3
	v_add_u32_e32 v3, 0x5000, v1
	global_load_lds_dwordx4 v[6:7], off
	v_lshl_add_u64 v[4:5], v[4:5], 0, v[8:9]
	s_mov_b32 m0, s2
	s_bitset1_b32 m0, 15
	v_readfirstlane_b32 s2, v3
	v_add_u32_e32 v3, 0x6000, v1
	global_load_lds_dwordx4 v[4:5], off
	v_lshl_add_u64 v[6:7], v[4:5], 0, s[24:25]
	s_mov_b32 m0, s2
	s_bitset1_b32 m0, 15
	v_readfirstlane_b32 s2, v3
	v_add_u32_e32 v1, 0x7000, v1
	global_load_lds_dwordx4 v[6:7], off
	v_lshl_add_u64 v[6:7], v[4:5], 0, s[26:27]
	s_mov_b32 m0, s2
	s_bitset1_b32 m0, 15
	v_readfirstlane_b32 s2, v1
	global_load_lds_dwordx4 v[6:7], off
	v_lshl_add_u64 v[4:5], v[4:5], 0, s[28:29]
	s_mov_b32 m0, s2
	s_bitset1_b32 m0, 15
	s_nop 0
	global_load_lds_dwordx4 v[4:5], off
.LBB0_121:
	v_mov_b32_e32 v1, v168
	v_readlane_b32 s60, v254, 48
	v_readfirstlane_b32 s2, v1
	s_lshl_b32 s3, s2, 5
	s_lshl_b32 s2, s2, 6
	s_and_b32 s3, s3, 0xfffff000
	s_and_b32 s2, s2, 0x1000
	v_readlane_b32 s64, v254, 52
	v_lshrrev_b32_e32 v3, 4, v1
	v_and_b32_e32 v4, 7, v1
	v_lshlrev_b32_e32 v1, 6, v1
	v_readlane_b32 s65, v254, 53
	s_add_u32 s50, s64, s50
	v_bitop3_b32 v3, v3, v4, 3 bitop3:0x6c
	s_waitcnt vmcnt(0)
	v_and_b32_e32 v1, 0x3c0, v1
	s_addc_u32 s51, s65, s51
	v_lshlrev_b32_e32 v69, 3, v3
	v_or_b32_e32 v3, s3, v1
	v_or_b32_e32 v4, s2, v1
	s_add_u32 s52, s64, s52
	s_waitcnt lgkmcnt(0)
	v_mov_b32_e32 v32, 0
	v_xor_b32_e32 v1, 32, v69
	s_addc_u32 s53, s65, s53
	s_mov_b64 s[54:55], 0
	s_mov_b32 s45, 0
	v_lshlrev_b32_e32 v3, 1, v3
	v_lshlrev_b32_e32 v68, 1, v4
	v_mov_b32_e32 v33, v32
	v_mov_b32_e32 v34, v32
	v_mov_b32_e32 v35, v32
	v_mov_b32_e32 v48, v32
	v_mov_b32_e32 v49, v32
	v_mov_b32_e32 v50, v32
	v_mov_b32_e32 v51, v32
	v_mov_b32_e32 v4, v32
	v_mov_b32_e32 v5, v32
	v_mov_b32_e32 v6, v32
	v_mov_b32_e32 v7, v32
	v_mov_b32_e32 v8, v32
	v_mov_b32_e32 v9, v32
	v_mov_b32_e32 v10, v32
	v_mov_b32_e32 v11, v32
	v_mov_b32_e32 v12, v32
	v_mov_b32_e32 v13, v32
	v_mov_b32_e32 v14, v32
	v_mov_b32_e32 v15, v32
	v_mov_b32_e32 v16, v32
	v_mov_b32_e32 v17, v32
	v_mov_b32_e32 v18, v32
	v_mov_b32_e32 v19, v32
	v_mov_b32_e32 v20, v32
	v_mov_b32_e32 v21, v32
	v_mov_b32_e32 v22, v32
	v_mov_b32_e32 v23, v32
	v_mov_b32_e32 v24, v32
	v_mov_b32_e32 v25, v32
	v_mov_b32_e32 v26, v32
	v_mov_b32_e32 v27, v32
	v_mov_b32_e32 v28, v32
	v_mov_b32_e32 v29, v32
	v_mov_b32_e32 v30, v32
	v_mov_b32_e32 v31, v32
	v_mov_b32_e32 v36, v32
	v_mov_b32_e32 v37, v32
	v_mov_b32_e32 v38, v32
	v_mov_b32_e32 v39, v32
	v_mov_b32_e32 v40, v32
	v_mov_b32_e32 v41, v32
	v_mov_b32_e32 v42, v32
	v_mov_b32_e32 v43, v32
	v_mov_b32_e32 v44, v32
	v_mov_b32_e32 v45, v32
	v_mov_b32_e32 v46, v32
	v_mov_b32_e32 v47, v32
	v_mov_b32_e32 v52, v32
	v_mov_b32_e32 v53, v32
	v_mov_b32_e32 v54, v32
	v_mov_b32_e32 v55, v32
	v_mov_b32_e32 v56, v32
	v_mov_b32_e32 v57, v32
	v_mov_b32_e32 v58, v32
	v_mov_b32_e32 v59, v32
	v_mov_b32_e32 v60, v32
	v_mov_b32_e32 v61, v32
	v_mov_b32_e32 v62, v32
	v_mov_b32_e32 v63, v32
	v_mov_b32_e32 v64, v32
	v_mov_b32_e32 v65, v32
	v_mov_b32_e32 v66, v32
	v_mov_b32_e32 v67, v32
	s_waitcnt vmcnt(0) lgkmcnt(0)
	s_barrier
	v_readlane_b32 s61, v254, 49
	v_readlane_b32 s62, v254, 50
	v_readlane_b32 s63, v254, 51
	v_readlane_b32 s66, v254, 54
	v_readlane_b32 s67, v254, 55
	v_lshlrev_b32_e32 v86, 1, v69
	v_add_u32_e32 v160, v3, v86
	v_add_u32_e32 v162, v68, v86
	v_lshlrev_b32_e32 v86, 1, v1
	v_add_u32_e32 v161, v3, v86
	v_add_u32_e32 v163, v68, v86
	v_lshrrev_b32_e32 v87, 3, v168
	v_xor_b32_e32 v86, v87, v168
	v_and_b32_e32 v86, 7, v86
	v_lshlrev_b32_e32 v86, 4, v86
	s_movk_i32 s60, 0x800
	v_mad_u32_u24 v164, v87, s60, v86
	v_add_u32_e32 v165, 0x10000, v164
	v_add_u32_e32 v166, 0x20000, v164
	v_add_u32_e32 v167, 0x30000, v164
	s_add_u32 s58, s50, s68
	s_addc_u32 s59, s51, s69
	s_add_u32 s34, s52, 0xa130080
	s_addc_u32 s35, s53, 0
	v_readfirstlane_b32 s60, v168
	s_lshl_b32 s60, s60, 4
	s_or_b32 s60, s60, 0x8000
	s_add_u32 s58, s58, 0x80
	s_addc_u32 s59, s59, 0
	s_add_u32 s34, s34, 0x80
	s_addc_u32 s35, s35, 0
	s_xor_b32 s60, s60, 0x8000

.Lv3_join_G6:
	s_add_u32 s54, s54, 0x80
	s_cmpk_eq_i32 s54, 0x780
	v_mfma_f32_16x16x32_bf16 v[24:27], v[152:155], v[128:131], v[24:27]
	v_mfma_f32_16x16x32_bf16 v[20:23], v[152:155], v[132:135], v[20:23]
	v_mfma_f32_16x16x32_bf16 v[16:19], v[152:155], v[136:139], v[16:19]
	v_mfma_f32_16x16x32_bf16 v[12:15], v[152:155], v[140:143], v[12:15]
	v_mfma_f32_16x16x32_bf16 v[8:11], v[156:159], v[128:131], v[8:11]
	v_mfma_f32_16x16x32_bf16 v[4:7], v[156:159], v[132:135], v[4:7]
	v_mfma_f32_16x16x32_bf16 v[48:51], v[156:159], v[136:139], v[48:51]
	v_mfma_f32_16x16x32_bf16 v[32:35], v[156:159], v[140:143], v[32:35]
	s_cbranch_scc0 .LBB0_122
	s_waitcnt vmcnt(0)
	s_barrier
	s_mov_b32 s37, 0x8000
	v_lshl_add_u32 v69, v69, 1, s37
	v_add_u32_e32 v102, v69, v68
	ds_read_b128 v[70:73], v102 offset:16384
	v_add_u32_e32 v69, v69, v3
	ds_read_b128 v[74:77], v69
	ds_read_b128 v[78:81], v69 offset:2048
	v_lshl_add_u32 v1, v1, 1, s37
	v_add_u32_e32 v68, v1, v68
	v_add_u32_e32 v1, v1, v3
	s_and_b64 vcc, exec, s[48:49]
	s_waitcnt lgkmcnt(0)
	v_mfma_f32_16x16x32_bf16 v[82:85], v[70:73], v[78:81], v[60:63]
	ds_read_b128 v[86:89], v69 offset:6144
	ds_read_b128 v[106:109], v1 offset:6144
	s_nop 0
	ds_read_b128 v[60:63], v69 offset:4096
	v_mfma_f32_16x16x32_bf16 v[64:67], v[70:73], v[74:77], v[64:67]
	s_waitcnt lgkmcnt(0)
	v_mfma_f32_16x16x32_bf16 v[56:59], v[70:73], v[60:63], v[56:59]
	v_mfma_f32_16x16x32_bf16 v[70:73], v[70:73], v[86:89], v[52:55]
	s_nop 2
	ds_read_b128 v[52:55], v102 offset:18432
	s_waitcnt lgkmcnt(0)
	v_mfma_f32_16x16x32_bf16 v[94:97], v[52:55], v[60:63], v[36:39]
	s_nop 2
	ds_read_b128 v[36:39], v102 offset:20480
	s_waitcnt lgkmcnt(0)
	v_mfma_f32_16x16x32_bf16 v[98:101], v[36:39], v[86:89], v[12:15]
	s_nop 2
	ds_read_b128 v[12:15], v102 offset:22528
	ds_read_b128 v[102:105], v1 offset:2048
	v_mfma_f32_16x16x32_bf16 v[90:93], v[52:55], v[74:77], v[44:47]
	v_mfma_f32_16x16x32_bf16 v[24:27], v[36:39], v[74:77], v[24:27]
	s_waitcnt lgkmcnt(1)
	v_mfma_f32_16x16x32_bf16 v[8:11], v[12:15], v[74:77], v[8:11]
	v_mfma_f32_16x16x32_bf16 v[74:77], v[12:15], v[78:81], v[4:7]
	s_nop 2
	ds_read_b128 v[4:7], v68 offset:16384
	v_mfma_f32_16x16x32_bf16 v[28:31], v[52:55], v[86:89], v[28:31]
	v_mfma_f32_16x16x32_bf16 v[86:89], v[12:15], v[86:89], v[32:35]
	s_nop 2
	ds_read_b128 v[32:35], v1
	v_mfma_f32_16x16x32_bf16 v[40:43], v[52:55], v[78:81], v[40:43]
	s_waitcnt lgkmcnt(1)
	v_mfma_f32_16x16x32_bf16 v[52:55], v[4:7], v[102:105], v[82:85]
	s_nop 2
	ds_read_b128 v[82:85], v1 offset:4096
	v_mfma_f32_16x16x32_bf16 v[20:23], v[36:39], v[78:81], v[20:23]
	v_mfma_f32_16x16x32_bf16 v[16:19], v[36:39], v[60:63], v[16:19]
	v_mfma_f32_16x16x32_bf16 v[78:81], v[12:15], v[60:63], v[48:51]
	s_waitcnt lgkmcnt(1)
	v_mfma_f32_16x16x32_bf16 v[60:63], v[4:7], v[32:35], v[64:67]
	s_waitcnt lgkmcnt(0)
	v_mfma_f32_16x16x32_bf16 v[44:47], v[4:7], v[82:85], v[56:59]
	v_mfma_f32_16x16x32_bf16 v[36:39], v[4:7], v[106:109], v[70:73]
	ds_read_b128 v[4:7], v68 offset:18432
	s_waitcnt lgkmcnt(0)
	v_mfma_f32_16x16x32_bf16 v[64:67], v[4:7], v[32:35], v[90:93]
	v_mfma_f32_16x16x32_bf16 v[56:59], v[4:7], v[102:105], v[40:43]
	v_mfma_f32_16x16x32_bf16 v[48:51], v[4:7], v[82:85], v[94:97]
	v_mfma_f32_16x16x32_bf16 v[40:43], v[4:7], v[106:109], v[28:31]
	ds_read_b128 v[4:7], v68 offset:20480
	ds_read_b128 v[68:71], v68 offset:22528
	s_waitcnt vmcnt(0)
	s_waitcnt lgkmcnt(1)
	v_mfma_f32_16x16x32_bf16 v[28:31], v[4:7], v[32:35], v[24:27]
	s_waitcnt lgkmcnt(0)
	s_barrier
	v_mfma_f32_16x16x32_bf16 v[20:23], v[4:7], v[102:105], v[20:23]
	v_mfma_f32_16x16x32_bf16 v[12:15], v[4:7], v[82:85], v[16:19]
	v_mfma_f32_16x16x32_bf16 v[4:7], v[4:7], v[106:109], v[98:101]
	v_mfma_f32_16x16x32_bf16 v[32:35], v[68:71], v[32:35], v[8:11]
	v_mfma_f32_16x16x32_bf16 v[24:27], v[68:71], v[102:105], v[74:77]
	v_mfma_f32_16x16x32_bf16 v[16:19], v[68:71], v[82:85], v[78:81]
	v_mfma_f32_16x16x32_bf16 v[8:11], v[68:71], v[106:109], v[86:89]
	s_cbranch_vccz .LBB0_125
	s_ashr_i32 s45, s44, 31
	v_mov_b32_e32 v1, v168
	s_lshl_b64 s[2:3], s[44:45], 18
	v_readlane_b32 s18, v252, 32
	v_readlane_b32 s19, v252, 33
	v_ashrrev_i32_e32 v68, 3, v1
	s_add_u32 s2, s18, s2
	v_xor_b32_e32 v3, v68, v1
	v_ashrrev_i32_e32 v69, 31, v68
	s_addc_u32 s3, s19, s3
	v_lshlrev_b64 v[68:69], 11, v[68:69]
	v_lshlrev_b32_e32 v3, 4, v3
	v_lshlrev_b32_e32 v1, 4, v1
	s_ashr_i32 s37, s36, 31
	v_lshl_add_u64 v[70:71], s[2:3], 0, v[68:69]
	v_and_b32_e32 v72, 0x70, v3
	v_mov_b32_e32 v73, v2
	v_readfirstlane_b32 s2, v1
	v_add_u32_e32 v3, 0x1000, v1
	s_lshl_b64 s[20:21], s[36:37], 18
	v_readlane_b32 s1, v252, 34
	v_lshl_add_u64 v[70:71], v[70:71], 0, v[72:73]
	s_mov_b32 m0, s2
	v_readfirstlane_b32 s2, v3
	v_add_u32_e32 v3, 0x2000, v1
	s_add_u32 s20, s1, s20
	v_readlane_b32 s1, v252, 35
	global_load_lds_dwordx4 v[70:71], off
	v_lshl_add_u64 v[74:75], v[70:71], 0, s[24:25]
	s_mov_b32 m0, s2
	v_readfirstlane_b32 s2, v3
	v_add_u32_e32 v3, 0x3000, v1
	s_addc_u32 s21, s1, s21
	global_load_lds_dwordx4 v[74:75], off
	v_lshl_add_u64 v[74:75], v[70:71], 0, s[26:27]
	s_mov_b32 m0, s2
	v_readfirstlane_b32 s2, v3
	v_add_u32_e32 v3, 0x4000, v1
	v_lshl_add_u64 v[68:69], s[20:21], 0, v[68:69]
	global_load_lds_dwordx4 v[74:75], off
	v_lshl_add_u64 v[70:71], v[70:71], 0, s[28:29]
	s_mov_b32 m0, s2
	v_readfirstlane_b32 s2, v3
	v_add_u32_e32 v3, 0x5000, v1
	global_load_lds_dwordx4 v[70:71], off
	v_lshl_add_u64 v[68:69], v[68:69], 0, v[72:73]
	s_mov_b32 m0, s2
	v_readfirstlane_b32 s2, v3
	v_add_u32_e32 v3, 0x6000, v1
	global_load_lds_dwordx4 v[68:69], off
	v_lshl_add_u64 v[70:71], v[68:69], 0, s[24:25]
	s_mov_b32 m0, s2
	v_readfirstlane_b32 s2, v3
	v_add_u32_e32 v1, 0x7000, v1
	global_load_lds_dwordx4 v[70:71], off
	v_lshl_add_u64 v[70:71], v[68:69], 0, s[26:27]
	s_mov_b32 m0, s2
	v_readfirstlane_b32 s2, v1
	global_load_lds_dwordx4 v[70:71], off
	v_lshl_add_u64 v[68:69], v[68:69], 0, s[28:29]
	s_mov_b32 m0, s2
	s_nop 0
	global_load_lds_dwordx4 v[68:69], off
	s_ashr_i32 s45, s44, 31
	v_mov_b32_e32 v1, v168
	s_lshl_b64 s[2:3], s[44:45], 18
	v_readlane_b32 s18, v252, 32
	v_readlane_b32 s19, v252, 33
	v_ashrrev_i32_e32 v68, 3, v1
	s_add_u32 s2, s18, s2
	v_xor_b32_e32 v3, v68, v1
	v_ashrrev_i32_e32 v69, 31, v68
	s_addc_u32 s3, s19, s3
	s_add_u32 s2, s2, 0x80
	s_addc_u32 s3, s3, 0
	v_lshlrev_b64 v[68:69], 11, v[68:69]
	v_lshlrev_b32_e32 v3, 4, v3
	v_lshlrev_b32_e32 v1, 4, v1
	s_ashr_i32 s37, s36, 31
	v_lshl_add_u64 v[70:71], s[2:3], 0, v[68:69]
	v_and_b32_e32 v72, 0x70, v3
	v_mov_b32_e32 v73, v2
	v_readfirstlane_b32 s2, v1
	v_add_u32_e32 v3, 0x1000, v1
	s_lshl_b64 s[20:21], s[36:37], 18
	v_readlane_b32 s1, v252, 34
	v_lshl_add_u64 v[70:71], v[70:71], 0, v[72:73]
	s_mov_b32 m0, s2
	s_bitset1_b32 m0, 15
	v_readfirstlane_b32 s2, v3
	v_add_u32_e32 v3, 0x2000, v1
	s_add_u32 s20, s1, s20
	v_readlane_b32 s1, v252, 35
	global_load_lds_dwordx4 v[70:71], off
	v_lshl_add_u64 v[74:75], v[70:71], 0, s[24:25]
	s_mov_b32 m0, s2
	s_bitset1_b32 m0, 15
	v_readfirstlane_b32 s2, v3
	v_add_u32_e32 v3, 0x3000, v1
	s_addc_u32 s21, s1, s21
	s_add_u32 s20, s20, 0x80
	s_addc_u32 s21, s21, 0
	global_load_lds_dwordx4 v[74:75], off
	v_lshl_add_u64 v[74:75], v[70:71], 0, s[26:27]
	s_mov_b32 m0, s2
	s_bitset1_b32 m0, 15
	v_readfirstlane_b32 s2, v3
	v_add_u32_e32 v3, 0x4000, v1
	v_lshl_add_u64 v[68:69], s[20:21], 0, v[68:69]
	global_load_lds_dwordx4 v[74:75], off
	v_lshl_add_u64 v[70:71], v[70:71], 0, s[28:29]
	s_mov_b32 m0, s2
	s_bitset1_b32 m0, 15
	v_readfirstlane_b32 s2, v3
	v_add_u32_e32 v3, 0x5000, v1
	global_load_lds_dwordx4 v[70:71], off
	v_lshl_add_u64 v[68:69], v[68:69], 0, v[72:73]
	s_mov_b32 m0, s2
	s_bitset1_b32 m0, 15
	v_readfirstlane_b32 s2, v3
	v_add_u32_e32 v3, 0x6000, v1
	global_load_lds_dwordx4 v[68:69], off
	v_lshl_add_u64 v[70:71], v[68:69], 0, s[24:25]
	s_mov_b32 m0, s2
	s_bitset1_b32 m0, 15
	v_readfirstlane_b32 s2, v3
	v_add_u32_e32 v1, 0x7000, v1
	global_load_lds_dwordx4 v[70:71], off
	v_lshl_add_u64 v[70:71], v[68:69], 0, s[26:27]
	s_mov_b32 m0, s2
	s_bitset1_b32 m0, 15
	v_readfirstlane_b32 s2, v1
	global_load_lds_dwordx4 v[70:71], off
	v_lshl_add_u64 v[68:69], v[68:69], 0, s[28:29]
	s_mov_b32 m0, s2
	s_bitset1_b32 m0, 15
	s_nop 0
	global_load_lds_dwordx4 v[68:69], off

.LBB0_624:
	s_lshl_b32 s38, s20, 7
	s_ashr_i32 s39, s38, 31
	s_andn2_b64 vcc, exec, s[48:49]
	s_lshl_b64 s[48:49], s[38:39], 11
	s_cbranch_vccnz .LBB0_626
	v_mov_b32_e32 v1, v168
	v_readlane_b32 s2, v252, 32
	v_readlane_b32 s3, v252, 33
	v_ashrrev_i32_e32 v4, 3, v1
	s_add_u32 s20, s2, s48
	v_xor_b32_e32 v3, v4, v1
	v_ashrrev_i32_e32 v5, 31, v4
	s_addc_u32 s21, s3, s49
	v_lshlrev_b64 v[4:5], 11, v[4:5]
	v_lshlrev_b32_e32 v3, 4, v3
	v_lshlrev_b32_e32 v1, 4, v1
	s_ashr_i32 s37, s36, 31
	s_waitcnt lgkmcnt(0)
	v_lshl_add_u64 v[6:7], s[20:21], 0, v[4:5]
	v_and_b32_e32 v8, 0x70, v3
	v_mov_b32_e32 v9, v2
	v_readfirstlane_b32 s2, v1
	v_add_u32_e32 v3, 0x1000, v1
	s_lshl_b64 s[50:51], s[36:37], 11
	v_readlane_b32 s1, v252, 19
	v_lshl_add_u64 v[6:7], v[6:7], 0, v[8:9]
	s_mov_b32 m0, s2
	v_readfirstlane_b32 s2, v3
	v_add_u32_e32 v3, 0x2000, v1
	s_add_u32 s52, s1, s50
	v_readlane_b32 s1, v252, 20
	global_load_lds_dwordx4 v[6:7], off
	v_lshl_add_u64 v[10:11], v[6:7], 0, s[24:25]
	s_mov_b32 m0, s2
	v_readfirstlane_b32 s2, v3
	v_add_u32_e32 v3, 0x3000, v1
	s_addc_u32 s53, s1, s51
	global_load_lds_dwordx4 v[10:11], off
	v_lshl_add_u64 v[10:11], v[6:7], 0, s[26:27]
	s_mov_b32 m0, s2
	v_readfirstlane_b32 s2, v3
	v_add_u32_e32 v3, 0x4000, v1
	v_lshl_add_u64 v[4:5], s[52:53], 0, v[4:5]
	global_load_lds_dwordx4 v[10:11], off
	v_lshl_add_u64 v[6:7], v[6:7], 0, s[28:29]
	s_mov_b32 m0, s2
	v_readfirstlane_b32 s2, v3
	v_add_u32_e32 v3, 0x5000, v1
	global_load_lds_dwordx4 v[6:7], off
	v_lshl_add_u64 v[4:5], v[4:5], 0, v[8:9]
	s_mov_b32 m0, s2
	v_readfirstlane_b32 s2, v3
	v_add_u32_e32 v3, 0x6000, v1
	global_load_lds_dwordx4 v[4:5], off
	v_lshl_add_u64 v[6:7], v[4:5], 0, s[24:25]
	s_mov_b32 m0, s2
	v_readfirstlane_b32 s2, v3
	v_add_u32_e32 v1, 0x7000, v1
	global_load_lds_dwordx4 v[6:7], off
	v_lshl_add_u64 v[6:7], v[4:5], 0, s[26:27]
	s_mov_b32 m0, s2
	v_readfirstlane_b32 s2, v1
	global_load_lds_dwordx4 v[6:7], off
	v_lshl_add_u64 v[4:5], v[4:5], 0, s[28:29]
	s_mov_b32 m0, s2
	s_nop 0
	global_load_lds_dwordx4 v[4:5], off
	v_mov_b32_e32 v1, v168
	v_readlane_b32 s2, v252, 32
	v_readlane_b32 s3, v252, 33
	v_ashrrev_i32_e32 v4, 3, v1
	s_add_u32 s20, s2, s48
	v_xor_b32_e32 v3, v4, v1
	v_ashrrev_i32_e32 v5, 31, v4
	s_addc_u32 s21, s3, s49
	s_add_u32 s20, s20, 0x80
	s_addc_u32 s21, s21, 0
	v_lshlrev_b64 v[4:5], 11, v[4:5]
	v_lshlrev_b32_e32 v3, 4, v3
	v_lshlrev_b32_e32 v1, 4, v1
	s_ashr_i32 s37, s36, 31
	s_waitcnt lgkmcnt(0)
	v_lshl_add_u64 v[6:7], s[20:21], 0, v[4:5]
	v_and_b32_e32 v8, 0x70, v3
	v_mov_b32_e32 v9, v2
	v_readfirstlane_b32 s2, v1
	v_add_u32_e32 v3, 0x1000, v1
	s_lshl_b64 s[50:51], s[36:37], 11
	v_readlane_b32 s1, v252, 19
	v_lshl_add_u64 v[6:7], v[6:7], 0, v[8:9]
	s_mov_b32 m0, s2
	s_bitset1_b32 m0, 15
	v_readfirstlane_b32 s2, v3
	v_add_u32_e32 v3, 0x2000, v1
	s_add_u32 s52, s1, s50
	v_readlane_b32 s1, v252, 20
	global_load_lds_dwordx4 v[6:7], off
	v_lshl_add_u64 v[10:11], v[6:7], 0, s[24:25]
	s_mov_b32 m0, s2
	s_bitset1_b32 m0, 15
	v_readfirstlane_b32 s2, v3
	v_add_u32_e32 v3, 0x3000, v1
	s_addc_u32 s53, s1, s51
	s_add_u32 s52, s52, 0x80
	s_addc_u32 s53, s53, 0
	global_load_lds_dwordx4 v[10:11], off
	v_lshl_add_u64 v[10:11], v[6:7], 0, s[26:27]
	s_mov_b32 m0, s2
	s_bitset1_b32 m0, 15
	v_readfirstlane_b32 s2, v3
	v_add_u32_e32 v3, 0x4000, v1
	v_lshl_add_u64 v[4:5], s[52:53], 0, v[4:5]
	global_load_lds_dwordx4 v[10:11], off
	v_lshl_add_u64 v[6:7], v[6:7], 0, s[28:29]
	s_mov_b32 m0, s2
	s_bitset1_b32 m0, 15
	v_readfirstlane_b32 s2, v3
	v_add_u32_e32 v3, 0x5000, v1
	global_load_lds_dwordx4 v[6:7], off
	v_lshl_add_u64 v[4:5], v[4:5], 0, v[8:9]
	s_mov_b32 m0, s2
	s_bitset1_b32 m0, 15
	v_readfirstlane_b32 s2, v3
	v_add_u32_e32 v3, 0x6000, v1
	global_load_lds_dwordx4 v[4:5], off
	v_lshl_add_u64 v[6:7], v[4:5], 0, s[24:25]
	s_mov_b32 m0, s2
	s_bitset1_b32 m0, 15
	v_readfirstlane_b32 s2, v3
	v_add_u32_e32 v1, 0x7000, v1
	global_load_lds_dwordx4 v[6:7], off
	v_lshl_add_u64 v[6:7], v[4:5], 0, s[26:27]
	s_mov_b32 m0, s2
	s_bitset1_b32 m0, 15
	v_readfirstlane_b32 s2, v1
	global_load_lds_dwordx4 v[6:7], off
	v_lshl_add_u64 v[4:5], v[4:5], 0, s[28:29]
	s_mov_b32 m0, s2
	s_bitset1_b32 m0, 15
	s_nop 0
	global_load_lds_dwordx4 v[4:5], off
.LBB0_626:
	v_mov_b32_e32 v1, v168
	v_readlane_b32 s56, v254, 48
	v_readfirstlane_b32 s2, v1
	s_lshl_b32 s3, s2, 5
	s_lshl_b32 s2, s2, 6
	s_and_b32 s3, s3, 0xfffff000
	s_and_b32 s2, s2, 0x1000
	v_readlane_b32 s60, v254, 52
	v_lshrrev_b32_e32 v3, 4, v1
	v_and_b32_e32 v4, 7, v1
	v_lshlrev_b32_e32 v1, 6, v1
	v_readlane_b32 s61, v254, 53
	s_add_u32 s48, s60, s48
	v_bitop3_b32 v3, v3, v4, 3 bitop3:0x6c
	s_waitcnt vmcnt(0)
	v_and_b32_e32 v1, 0x3c0, v1
	s_addc_u32 s49, s61, s49
	v_lshlrev_b32_e32 v69, 3, v3
	v_or_b32_e32 v3, s3, v1
	v_or_b32_e32 v4, s2, v1
	s_add_u32 s50, s60, s50
	s_waitcnt lgkmcnt(0)
	v_mov_b32_e32 v32, 0
	v_xor_b32_e32 v1, 32, v69
	s_addc_u32 s51, s61, s51
	s_mov_b64 s[52:53], 0
	s_mov_b32 s41, 0
	v_lshlrev_b32_e32 v3, 1, v3
	v_lshlrev_b32_e32 v68, 1, v4
	v_mov_b32_e32 v33, v32
	v_mov_b32_e32 v34, v32
	v_mov_b32_e32 v35, v32
	v_mov_b32_e32 v48, v32
	v_mov_b32_e32 v49, v32
	v_mov_b32_e32 v50, v32
	v_mov_b32_e32 v51, v32
	v_mov_b32_e32 v4, v32
	v_mov_b32_e32 v5, v32
	v_mov_b32_e32 v6, v32
	v_mov_b32_e32 v7, v32
	v_mov_b32_e32 v8, v32
	v_mov_b32_e32 v9, v32
	v_mov_b32_e32 v10, v32
	v_mov_b32_e32 v11, v32
	v_mov_b32_e32 v12, v32
	v_mov_b32_e32 v13, v32
	v_mov_b32_e32 v14, v32
	v_mov_b32_e32 v15, v32
	v_mov_b32_e32 v16, v32
	v_mov_b32_e32 v17, v32
	v_mov_b32_e32 v18, v32
	v_mov_b32_e32 v19, v32
	v_mov_b32_e32 v20, v32
	v_mov_b32_e32 v21, v32
	v_mov_b32_e32 v22, v32
	v_mov_b32_e32 v23, v32
	v_mov_b32_e32 v24, v32
	v_mov_b32_e32 v25, v32
	v_mov_b32_e32 v26, v32
	v_mov_b32_e32 v27, v32
	v_mov_b32_e32 v28, v32
	v_mov_b32_e32 v29, v32
	v_mov_b32_e32 v30, v32
	v_mov_b32_e32 v31, v32
	v_mov_b32_e32 v36, v32
	v_mov_b32_e32 v37, v32
	v_mov_b32_e32 v38, v32
	v_mov_b32_e32 v39, v32
	v_mov_b32_e32 v40, v32
	v_mov_b32_e32 v41, v32
	v_mov_b32_e32 v42, v32
	v_mov_b32_e32 v43, v32
	v_mov_b32_e32 v44, v32
	v_mov_b32_e32 v45, v32
	v_mov_b32_e32 v46, v32
	v_mov_b32_e32 v47, v32
	v_mov_b32_e32 v52, v32
	v_mov_b32_e32 v53, v32
	v_mov_b32_e32 v54, v32
	v_mov_b32_e32 v55, v32
	v_mov_b32_e32 v56, v32
	v_mov_b32_e32 v57, v32
	v_mov_b32_e32 v58, v32
	v_mov_b32_e32 v59, v32
	v_mov_b32_e32 v60, v32
	v_mov_b32_e32 v61, v32
	v_mov_b32_e32 v62, v32
	v_mov_b32_e32 v63, v32
	v_mov_b32_e32 v64, v32
	v_mov_b32_e32 v65, v32
	v_mov_b32_e32 v66, v32
	v_mov_b32_e32 v67, v32
	s_waitcnt vmcnt(0)
	s_barrier
	v_readlane_b32 s57, v254, 49
	v_readlane_b32 s58, v254, 50
	v_readlane_b32 s59, v254, 51
	v_readlane_b32 s62, v254, 54
	v_readlane_b32 s63, v254, 55
	v_lshlrev_b32_e32 v86, 1, v69
	v_add_u32_e32 v160, v3, v86
	v_add_u32_e32 v162, v68, v86
	v_lshlrev_b32_e32 v86, 1, v1
	v_add_u32_e32 v161, v3, v86
	v_add_u32_e32 v163, v68, v86
	v_lshrrev_b32_e32 v87, 3, v168
	v_xor_b32_e32 v86, v87, v168
	v_and_b32_e32 v86, 7, v86
	v_lshlrev_b32_e32 v86, 4, v86
	s_movk_i32 s60, 0x800
	v_mad_u32_u24 v164, v87, s60, v86
	v_add_u32_e32 v165, 0x10000, v164
	v_add_u32_e32 v166, 0x20000, v164
	v_add_u32_e32 v167, 0x30000, v164
	s_add_u32 s56, s48, s68
	s_addc_u32 s57, s49, s69
	s_add_u32 s58, s50, 0x80080
	s_addc_u32 s59, s51, 0
	v_readfirstlane_b32 s60, v168
	s_lshl_b32 s60, s60, 4
	s_or_b32 s60, s60, 0x8000
	s_add_u32 s56, s56, 0x80
	s_addc_u32 s57, s57, 0
	s_add_u32 s58, s58, 0x80
	s_addc_u32 s59, s59, 0
	s_xor_b32 s60, s60, 0x8000

.Lv3_join_G1:
	s_add_u32 s52, s52, 0x80
	s_cmpk_eq_i32 s52, 0x780
	v_mfma_f32_16x16x32_bf16 v[24:27], v[152:155], v[128:131], v[24:27]
	v_mfma_f32_16x16x32_bf16 v[20:23], v[152:155], v[132:135], v[20:23]
	v_mfma_f32_16x16x32_bf16 v[16:19], v[152:155], v[136:139], v[16:19]
	v_mfma_f32_16x16x32_bf16 v[12:15], v[152:155], v[140:143], v[12:15]
	v_mfma_f32_16x16x32_bf16 v[8:11], v[156:159], v[128:131], v[8:11]
	v_mfma_f32_16x16x32_bf16 v[4:7], v[156:159], v[132:135], v[4:7]
	v_mfma_f32_16x16x32_bf16 v[48:51], v[156:159], v[136:139], v[48:51]
	v_mfma_f32_16x16x32_bf16 v[32:35], v[156:159], v[140:143], v[32:35]
	s_cbranch_scc0 .LBB0_627
	s_waitcnt vmcnt(0)
	s_barrier
	s_mov_b32 s37, 0x8000
	v_lshl_add_u32 v69, v69, 1, s37
	v_add_u32_e32 v90, v69, v68
	ds_read_b128 v[70:73], v90 offset:16384
	v_add_u32_e32 v69, v69, v3
	ds_read_b128 v[74:77], v69
	ds_read_b128 v[78:81], v69 offset:2048
	ds_read_b128 v[82:85], v69 offset:4096
	ds_read_b128 v[86:89], v69 offset:6144
	v_lshl_add_u32 v1, v1, 1, s37
	v_add_u32_e32 v98, v1, v68
	ds_read_b128 v[94:97], v98 offset:20480
	s_waitcnt lgkmcnt(4)
	v_mfma_f32_16x16x32_bf16 v[64:67], v[70:73], v[74:77], v[64:67]
	v_add_u32_e32 v1, v1, v3
	s_and_b64 vcc, exec, s[46:47]
	s_waitcnt lgkmcnt(3)
	v_mfma_f32_16x16x32_bf16 v[60:63], v[70:73], v[78:81], v[60:63]
	s_waitcnt lgkmcnt(2)
	v_mfma_f32_16x16x32_bf16 v[56:59], v[70:73], v[82:85], v[56:59]
	s_waitcnt lgkmcnt(1)
	v_mfma_f32_16x16x32_bf16 v[52:55], v[70:73], v[86:89], v[52:55]
	ds_read_b128 v[70:73], v90 offset:18432
	s_waitcnt lgkmcnt(0)
	v_mfma_f32_16x16x32_bf16 v[44:47], v[70:73], v[74:77], v[44:47]
	v_mfma_f32_16x16x32_bf16 v[40:43], v[70:73], v[78:81], v[40:43]
	v_mfma_f32_16x16x32_bf16 v[36:39], v[70:73], v[82:85], v[36:39]
	v_mfma_f32_16x16x32_bf16 v[28:31], v[70:73], v[86:89], v[28:31]
	ds_read_b128 v[70:73], v90 offset:20480
	s_waitcnt lgkmcnt(0)
	v_mfma_f32_16x16x32_bf16 v[24:27], v[70:73], v[74:77], v[24:27]
	v_mfma_f32_16x16x32_bf16 v[20:23], v[70:73], v[78:81], v[20:23]
	v_mfma_f32_16x16x32_bf16 v[16:19], v[70:73], v[82:85], v[16:19]
	v_mfma_f32_16x16x32_bf16 v[12:15], v[70:73], v[86:89], v[12:15]
	ds_read_b128 v[70:73], v90 offset:22528
	ds_read_b128 v[90:93], v1 offset:6144
	s_waitcnt lgkmcnt(1)
	v_mfma_f32_16x16x32_bf16 v[8:11], v[70:73], v[74:77], v[8:11]
	v_mfma_f32_16x16x32_bf16 v[4:7], v[70:73], v[78:81], v[4:7]
	ds_read_b128 v[78:81], v1
	v_mfma_f32_16x16x32_bf16 v[74:77], v[70:73], v[82:85], v[48:51]
	ds_read_b128 v[82:85], v1 offset:2048
	s_nop 1
	ds_read_b128 v[48:51], v98 offset:16384
	v_mfma_f32_16x16x32_bf16 v[68:71], v[70:73], v[86:89], v[32:35]
	ds_read_b128 v[86:89], v1 offset:4096
	s_nop 1
	ds_read_b128 v[32:35], v98 offset:18432
	s_waitcnt lgkmcnt(2)
	v_mfma_f32_16x16x32_bf16 v[64:67], v[48:51], v[78:81], v[64:67]
	v_mfma_f32_16x16x32_bf16 v[60:63], v[48:51], v[82:85], v[60:63]
	s_waitcnt lgkmcnt(1)
	v_mfma_f32_16x16x32_bf16 v[56:59], v[48:51], v[86:89], v[56:59]
	v_mfma_f32_16x16x32_bf16 v[52:55], v[48:51], v[90:93], v[52:55]
	s_waitcnt lgkmcnt(0)
	v_mfma_f32_16x16x32_bf16 v[48:51], v[32:35], v[78:81], v[44:47]
	v_mfma_f32_16x16x32_bf16 v[44:47], v[32:35], v[82:85], v[40:43]
	v_mfma_f32_16x16x32_bf16 v[40:43], v[32:35], v[86:89], v[36:39]
	v_mfma_f32_16x16x32_bf16 v[36:39], v[32:35], v[90:93], v[28:31]
	v_mfma_f32_16x16x32_bf16 v[32:35], v[94:97], v[78:81], v[24:27]
	v_mfma_f32_16x16x32_bf16 v[28:31], v[94:97], v[82:85], v[20:23]
	v_mfma_f32_16x16x32_bf16 v[24:27], v[94:97], v[86:89], v[16:19]
	v_mfma_f32_16x16x32_bf16 v[20:23], v[94:97], v[90:93], v[12:15]
	ds_read_b128 v[94:97], v98 offset:22528
	s_waitcnt vmcnt(0)
	s_waitcnt lgkmcnt(0)
	v_mfma_f32_16x16x32_bf16 v[16:19], v[94:97], v[78:81], v[8:11]
	s_barrier
	v_mfma_f32_16x16x32_bf16 v[12:15], v[94:97], v[82:85], v[4:7]
	v_mfma_f32_16x16x32_bf16 v[8:11], v[94:97], v[86:89], v[74:77]
	v_mfma_f32_16x16x32_bf16 v[4:7], v[94:97], v[90:93], v[68:71]
	s_cbranch_vccz .LBB0_630
	s_ashr_i32 s41, s40, 31
	v_mov_b32_e32 v1, v168
	s_lshl_b64 s[20:21], s[40:41], 18
	v_readlane_b32 s2, v252, 32
	v_readlane_b32 s3, v252, 33
	v_ashrrev_i32_e32 v68, 3, v1
	s_add_u32 s20, s2, s20
	v_xor_b32_e32 v3, v68, v1
	v_ashrrev_i32_e32 v69, 31, v68
	s_addc_u32 s21, s3, s21
	v_lshlrev_b64 v[68:69], 11, v[68:69]
	v_lshlrev_b32_e32 v3, 4, v3
	v_lshlrev_b32_e32 v1, 4, v1
	s_ashr_i32 s43, s42, 31
	v_lshl_add_u64 v[70:71], s[20:21], 0, v[68:69]
	v_and_b32_e32 v72, 0x70, v3
	v_mov_b32_e32 v73, v2
	v_readfirstlane_b32 s2, v1
	v_add_u32_e32 v3, 0x1000, v1
	s_lshl_b64 s[46:47], s[42:43], 18
	v_readlane_b32 s1, v252, 19
	v_lshl_add_u64 v[70:71], v[70:71], 0, v[72:73]
	s_mov_b32 m0, s2
	v_readfirstlane_b32 s2, v3
	v_add_u32_e32 v3, 0x2000, v1
	s_add_u32 s46, s1, s46
	v_readlane_b32 s1, v252, 20
	global_load_lds_dwordx4 v[70:71], off
	v_lshl_add_u64 v[74:75], v[70:71], 0, s[24:25]
	s_mov_b32 m0, s2
	v_readfirstlane_b32 s2, v3
	v_add_u32_e32 v3, 0x3000, v1
	s_addc_u32 s47, s1, s47
	global_load_lds_dwordx4 v[74:75], off
	v_lshl_add_u64 v[74:75], v[70:71], 0, s[26:27]
	s_mov_b32 m0, s2
	v_readfirstlane_b32 s2, v3
	v_add_u32_e32 v3, 0x4000, v1
	v_lshl_add_u64 v[68:69], s[46:47], 0, v[68:69]
	global_load_lds_dwordx4 v[74:75], off
	v_lshl_add_u64 v[70:71], v[70:71], 0, s[28:29]
	s_mov_b32 m0, s2
	v_readfirstlane_b32 s2, v3
	v_add_u32_e32 v3, 0x5000, v1
	global_load_lds_dwordx4 v[70:71], off
	v_lshl_add_u64 v[68:69], v[68:69], 0, v[72:73]
	s_mov_b32 m0, s2
	v_readfirstlane_b32 s2, v3
	v_add_u32_e32 v3, 0x6000, v1
	global_load_lds_dwordx4 v[68:69], off
	v_lshl_add_u64 v[70:71], v[68:69], 0, s[24:25]
	s_mov_b32 m0, s2
	v_readfirstlane_b32 s2, v3
	v_add_u32_e32 v1, 0x7000, v1
	global_load_lds_dwordx4 v[70:71], off
	v_lshl_add_u64 v[70:71], v[68:69], 0, s[26:27]
	s_mov_b32 m0, s2
	v_readfirstlane_b32 s2, v1
	global_load_lds_dwordx4 v[70:71], off
	v_lshl_add_u64 v[68:69], v[68:69], 0, s[28:29]
	s_mov_b32 m0, s2
	s_nop 0
	global_load_lds_dwordx4 v[68:69], off
	s_ashr_i32 s41, s40, 31
	v_mov_b32_e32 v1, v168
	s_lshl_b64 s[20:21], s[40:41], 18
	v_readlane_b32 s2, v252, 32
	v_readlane_b32 s3, v252, 33
	v_ashrrev_i32_e32 v68, 3, v1
	s_add_u32 s20, s2, s20
	v_xor_b32_e32 v3, v68, v1
	v_ashrrev_i32_e32 v69, 31, v68
	s_addc_u32 s21, s3, s21
	s_add_u32 s20, s20, 0x80
	s_addc_u32 s21, s21, 0
	v_lshlrev_b64 v[68:69], 11, v[68:69]
	v_lshlrev_b32_e32 v3, 4, v3
	v_lshlrev_b32_e32 v1, 4, v1
	s_ashr_i32 s43, s42, 31
	v_lshl_add_u64 v[70:71], s[20:21], 0, v[68:69]
	v_and_b32_e32 v72, 0x70, v3
	v_mov_b32_e32 v73, v2
	v_readfirstlane_b32 s2, v1
	v_add_u32_e32 v3, 0x1000, v1
	s_lshl_b64 s[46:47], s[42:43], 18
	v_readlane_b32 s1, v252, 19
	v_lshl_add_u64 v[70:71], v[70:71], 0, v[72:73]
	s_mov_b32 m0, s2
	s_bitset1_b32 m0, 15
	v_readfirstlane_b32 s2, v3
	v_add_u32_e32 v3, 0x2000, v1
	s_add_u32 s46, s1, s46
	v_readlane_b32 s1, v252, 20
	global_load_lds_dwordx4 v[70:71], off
	v_lshl_add_u64 v[74:75], v[70:71], 0, s[24:25]
	s_mov_b32 m0, s2
	s_bitset1_b32 m0, 15
	v_readfirstlane_b32 s2, v3
	v_add_u32_e32 v3, 0x3000, v1
	s_addc_u32 s47, s1, s47
	s_add_u32 s46, s46, 0x80
	s_addc_u32 s47, s47, 0
	global_load_lds_dwordx4 v[74:75], off
	v_lshl_add_u64 v[74:75], v[70:71], 0, s[26:27]
	s_mov_b32 m0, s2
	s_bitset1_b32 m0, 15
	v_readfirstlane_b32 s2, v3
	v_add_u32_e32 v3, 0x4000, v1
	v_lshl_add_u64 v[68:69], s[46:47], 0, v[68:69]
	global_load_lds_dwordx4 v[74:75], off
	v_lshl_add_u64 v[70:71], v[70:71], 0, s[28:29]
	s_mov_b32 m0, s2
	s_bitset1_b32 m0, 15
	v_readfirstlane_b32 s2, v3
	v_add_u32_e32 v3, 0x5000, v1
	global_load_lds_dwordx4 v[70:71], off
	v_lshl_add_u64 v[68:69], v[68:69], 0, v[72:73]
	s_mov_b32 m0, s2
	s_bitset1_b32 m0, 15
	v_readfirstlane_b32 s2, v3
	v_add_u32_e32 v3, 0x6000, v1
	global_load_lds_dwordx4 v[68:69], off
	v_lshl_add_u64 v[70:71], v[68:69], 0, s[24:25]
	s_mov_b32 m0, s2
	s_bitset1_b32 m0, 15
	v_readfirstlane_b32 s2, v3
	v_add_u32_e32 v1, 0x7000, v1
	global_load_lds_dwordx4 v[70:71], off
	v_lshl_add_u64 v[70:71], v[68:69], 0, s[26:27]
	s_mov_b32 m0, s2
	s_bitset1_b32 m0, 15
	v_readfirstlane_b32 s2, v1
	global_load_lds_dwordx4 v[70:71], off
	v_lshl_add_u64 v[68:69], v[68:69], 0, s[28:29]
	s_mov_b32 m0, s2
	s_bitset1_b32 m0, 15
	s_nop 0
	global_load_lds_dwordx4 v[68:69], off
